# phase 2 windowed-attention tiles: LDS fragment reads of each QK/PV MFMA run hoisted (six fragments in flight, v234-243/248-255)
# speedup vs baseline: 1.0021x; 1.0021x over previous
.LBB0_760:
	v_add_f32_e32 v0, 0, v3
	v_add_f32_e32 v0, v4, v0
	v_add_f32_e32 v0, v5, v0
	v_add_f32_e32 v0, v6, v0
	v_add_f32_e32 v0, v7, v0
	v_add_f32_e32 v0, v8, v0
	v_add_f32_e32 v0, v9, v0
	v_add_f32_e32 v0, v10, v0
	v_add_f32_e32 v0, v11, v0
	v_add_f32_e32 v0, v12, v0
	v_add_f32_e32 v0, v13, v0
	v_add_f32_e32 v0, v14, v0
	v_add_f32_e32 v0, v15, v0
	v_add_f32_e32 v0, v48, v0
	v_add_f32_e32 v0, v49, v0
	v_add_f32_e32 v0, v50, v0
	v_add_f32_e32 v0, v51, v0
	v_add_f32_e32 v0, v52, v0
	v_add_f32_e32 v0, v53, v0
	v_add_f32_e32 v0, v54, v0
	v_add_f32_e32 v0, v55, v0
	v_add_f32_e32 v0, v56, v0
	v_add_f32_e32 v0, v57, v0
	v_add_f32_e32 v0, v58, v0
	v_add_f32_e32 v0, v59, v0
	v_add_f32_e32 v0, v60, v0
	v_add_f32_e32 v0, v61, v0
	v_add_f32_e32 v0, v62, v0
	s_waitcnt lgkmcnt(0)
	s_barrier
	ds_read_b128 v[4:7], v145 offset:18432
	ds_read_b128 v[8:11], v145 offset:18464
	ds_read_b128 v[234:237], v145 offset:23040
	ds_read_b128 v[238:241], v145 offset:23072
	ds_read_b128 v[248:251], v145 offset:18496
	ds_read_b128 v[252:255], v145 offset:23104
	v_add_f32_e32 v0, v63, v0
	v_add_f32_e32 v0, v64, v0
	v_add_f32_e32 v0, v65, v0
	v_add_f32_e32 v0, v66, v0
	s_waitcnt lgkmcnt(5)
	v_mfma_f32_32x32x16_bf16 v[64:79], v[4:7], v[80:83], 0
	ds_read_b128 v[4:7], v145 offset:18528
	s_mov_b32 s10, 0xf149f2ca
	v_add_f32_e32 v0, v166, v0
	s_waitcnt lgkmcnt(4)
	v_mfma_f32_32x32x16_bf16 v[48:63], v[234:237], v[80:83], 0
	ds_read_b128 v[234:237], v145 offset:23136
	s_waitcnt lgkmcnt(4)
	v_mfma_f32_32x32x16_bf16 v[48:63], v[238:241], v[84:87], v[48:63]
	s_nop 0
	v_mfma_f32_32x32x16_bf16 v[64:79], v[8:11], v[84:87], v[64:79]
	s_waitcnt lgkmcnt(3)
	v_mfma_f32_32x32x16_bf16 v[64:79], v[248:251], v[88:91], v[64:79]
	s_waitcnt lgkmcnt(2)
	v_mfma_f32_32x32x16_bf16 v[48:63], v[252:255], v[88:91], v[48:63]
	s_waitcnt lgkmcnt(1)
	v_mfma_f32_32x32x16_bf16 v[64:79], v[4:7], v[92:95], v[64:79]
	s_waitcnt lgkmcnt(0)
	v_mfma_f32_32x32x16_bf16 v[48:63], v[234:237], v[92:95], v[48:63]
	s_nop 8
	v_mul_f32_e32 v174, 0x3e38aa3b, v64
	v_mul_f32_e32 v173, 0x3e38aa3b, v65
	v_max3_f32 v3, v174, s10, v173
	v_mul_f32_e32 v172, 0x3e38aa3b, v66
	v_mul_f32_e32 v171, 0x3e38aa3b, v67
	v_max3_f32 v3, v3, v172, v171
	v_mul_f32_e32 v170, 0x3e38aa3b, v68
	v_mul_f32_e32 v169, 0x3e38aa3b, v69
	v_max3_f32 v3, v3, v170, v169
	v_mul_f32_e32 v168, 0x3e38aa3b, v70
	v_mul_f32_e32 v166, 0x3e38aa3b, v71
	v_max3_f32 v3, v3, v168, v166
	v_mul_f32_e32 v72, 0x3e38aa3b, v72
	v_mul_f32_e32 v71, 0x3e38aa3b, v73
	v_max3_f32 v3, v3, v72, v71
	v_mul_f32_e32 v70, 0x3e38aa3b, v74
	v_mul_f32_e32 v69, 0x3e38aa3b, v75
	v_max3_f32 v3, v3, v70, v69
	v_mul_f32_e32 v68, 0x3e38aa3b, v76
	v_mul_f32_e32 v67, 0x3e38aa3b, v77
	v_max3_f32 v3, v3, v68, v67
	v_mul_f32_e32 v66, 0x3e38aa3b, v78
	v_mul_f32_e32 v65, 0x3e38aa3b, v79
	v_max3_f32 v3, v3, v66, v65
	v_mul_f32_e32 v64, 0x3e38aa3b, v48
	v_mul_f32_e32 v49, 0x3e38aa3b, v49
	v_max3_f32 v3, v3, v64, v49
	v_mul_f32_e32 v48, 0x3e38aa3b, v50
	v_mul_f32_e32 v15, 0x3e38aa3b, v51
	v_max3_f32 v3, v3, v48, v15
	v_mul_f32_e32 v14, 0x3e38aa3b, v52
	v_mul_f32_e32 v13, 0x3e38aa3b, v53
	v_max3_f32 v3, v3, v14, v13
	v_mul_f32_e32 v12, 0x3e38aa3b, v54
	v_mul_f32_e32 v11, 0x3e38aa3b, v55
	v_max3_f32 v3, v3, v12, v11
	v_mul_f32_e32 v10, 0x3e38aa3b, v56
	v_mul_f32_e32 v9, 0x3e38aa3b, v57
	v_max3_f32 v3, v3, v10, v9
	v_mul_f32_e32 v8, 0x3e38aa3b, v58
	v_mul_f32_e32 v7, 0x3e38aa3b, v59
	v_max3_f32 v3, v3, v8, v7
	v_mul_f32_e32 v6, 0x3e38aa3b, v60
	v_mul_f32_e32 v5, 0x3e38aa3b, v61
	v_max3_f32 v50, v3, v6, v5
	v_mul_f32_e32 v4, 0x3e38aa3b, v62
	v_mul_f32_e32 v3, 0x3e38aa3b, v63
	v_max3_f32 v50, v50, v4, v3
	ds_bpermute_b32 v51, v142, v50
	s_waitcnt lgkmcnt(0)
	v_max3_f32 v167, v2, v50, v51
	v_cmp_gt_f32_e32 vcc, v167, v2
	s_cbranch_vccz .LBB0_769
	v_sub_f32_e32 v2, v2, v167
	v_exp_f32_e32 v2, v2
	s_nop 0
	v_mul_f32_e32 v0, v0, v2
	v_pk_mul_f32 v[46:47], v[46:47], v[2:3] op_sel_hi:[1,0]
	v_pk_mul_f32 v[44:45], v[44:45], v[2:3] op_sel_hi:[1,0]
	v_pk_mul_f32 v[42:43], v[42:43], v[2:3] op_sel_hi:[1,0]
	v_pk_mul_f32 v[40:41], v[40:41], v[2:3] op_sel_hi:[1,0]
	v_pk_mul_f32 v[38:39], v[38:39], v[2:3] op_sel_hi:[1,0]
	v_pk_mul_f32 v[36:37], v[36:37], v[2:3] op_sel_hi:[1,0]
	v_pk_mul_f32 v[34:35], v[34:35], v[2:3] op_sel_hi:[1,0]
	v_pk_mul_f32 v[32:33], v[32:33], v[2:3] op_sel_hi:[1,0]
	v_pk_mul_f32 v[30:31], v[30:31], v[2:3] op_sel_hi:[1,0]
	v_pk_mul_f32 v[28:29], v[28:29], v[2:3] op_sel_hi:[1,0]
	v_pk_mul_f32 v[26:27], v[26:27], v[2:3] op_sel_hi:[1,0]
	v_pk_mul_f32 v[24:25], v[24:25], v[2:3] op_sel_hi:[1,0]
	v_pk_mul_f32 v[22:23], v[22:23], v[2:3] op_sel_hi:[1,0]
	v_pk_mul_f32 v[20:21], v[20:21], v[2:3] op_sel_hi:[1,0]
	v_pk_mul_f32 v[18:19], v[18:19], v[2:3] op_sel_hi:[1,0]
	v_pk_mul_f32 v[16:17], v[16:17], v[2:3] op_sel_hi:[1,0]
.LBB0_762:
	v_sub_f32_e32 v2, v174, v167
	v_exp_f32_e32 v2, v2
	v_sub_f32_e32 v51, v173, v167
	v_exp_f32_e32 v51, v51
	v_sub_f32_e32 v52, v172, v167
	v_exp_f32_e32 v52, v52
	v_sub_f32_e32 v53, v171, v167
	v_exp_f32_e32 v53, v53
	v_sub_f32_e32 v54, v170, v167
	v_add_f32_e32 v50, 0, v2
	v_exp_f32_e32 v54, v54
	v_sub_f32_e32 v55, v169, v167
	v_add_f32_e32 v50, v51, v50
	v_exp_f32_e32 v55, v55
	v_sub_f32_e32 v56, v168, v167
	v_add_f32_e32 v50, v52, v50
	v_exp_f32_e32 v56, v56
	v_sub_f32_e32 v57, v166, v167
	v_add_f32_e32 v50, v53, v50
	v_exp_f32_e32 v57, v57
	v_sub_f32_e32 v58, v72, v167
	v_add_f32_e32 v50, v54, v50
	v_exp_f32_e32 v58, v58
	v_sub_f32_e32 v59, v71, v167
	v_add_f32_e32 v50, v55, v50
	v_exp_f32_e32 v59, v59
	v_sub_f32_e32 v60, v70, v167
	v_add_f32_e32 v50, v56, v50
	v_exp_f32_e32 v60, v60
	v_sub_f32_e32 v61, v69, v167
	v_add_f32_e32 v50, v57, v50
	v_exp_f32_e32 v61, v61
	v_sub_f32_e32 v62, v68, v167
	v_add_f32_e32 v50, v58, v50
	v_exp_f32_e32 v62, v62
	v_sub_f32_e32 v63, v67, v167
	v_add_f32_e32 v50, v59, v50
	v_exp_f32_e32 v63, v63
	v_sub_f32_e32 v66, v66, v167
	v_add_f32_e32 v50, v60, v50
	v_exp_f32_e32 v66, v66
	v_sub_f32_e32 v65, v65, v167
	v_add_f32_e32 v50, v61, v50
	v_exp_f32_e32 v65, v65
	v_sub_f32_e32 v64, v64, v167
	v_add_f32_e32 v50, v62, v50
	v_exp_f32_e32 v64, v64
	v_sub_f32_e32 v49, v49, v167
	v_add_f32_e32 v50, v63, v50
	v_exp_f32_e32 v49, v49
	v_sub_f32_e32 v48, v48, v167
	v_add_f32_e32 v50, v66, v50
	v_exp_f32_e32 v48, v48
	v_sub_f32_e32 v15, v15, v167
	v_add_f32_e32 v50, v65, v50
	v_exp_f32_e32 v15, v15
	v_sub_f32_e32 v14, v14, v167
	v_add_f32_e32 v50, v64, v50
	v_exp_f32_e32 v14, v14
	v_sub_f32_e32 v13, v13, v167
	v_add_f32_e32 v50, v49, v50
	v_exp_f32_e32 v13, v13
	v_sub_f32_e32 v12, v12, v167
	v_add_f32_e32 v50, v48, v50
	v_exp_f32_e32 v12, v12
	v_sub_f32_e32 v11, v11, v167
	v_add_f32_e32 v50, v15, v50
	v_exp_f32_e32 v11, v11
	v_sub_f32_e32 v10, v10, v167
	v_add_f32_e32 v50, v14, v50
	v_exp_f32_e32 v10, v10
	v_sub_f32_e32 v9, v9, v167
	v_add_f32_e32 v50, v13, v50
	v_exp_f32_e32 v67, v9
	v_add_f32_e32 v50, v12, v50
	v_add_f32_e32 v50, v11, v50
	v_add_f32_e32 v50, v10, v50
	v_sub_f32_e32 v8, v8, v167
	v_add_f32_e32 v9, v67, v50
	v_exp_f32_e32 v50, v8
	v_sub_f32_e32 v7, v7, v167
	v_exp_f32_e32 v68, v7
	v_sub_f32_e32 v6, v6, v167
	v_exp_f32_e32 v69, v6
	v_sub_f32_e32 v5, v5, v167
	v_exp_f32_e32 v70, v5
	v_add_f32_e32 v8, v50, v9
	v_sub_f32_e32 v4, v4, v167
	v_add_f32_e32 v7, v68, v8
	v_exp_f32_e32 v71, v4
	v_sub_f32_e32 v3, v3, v167
	v_add_f32_e32 v6, v69, v7
	v_exp_f32_e32 v72, v3
	v_add_f32_e32 v5, v70, v6
	ds_read_b64 v[6:7], v146 offset:27648
	ds_read_b64 v[8:9], v147 offset:27648
	ds_read_b64 v[234:235], v148 offset:32256
	ds_read_b64 v[236:237], v149 offset:32256
	ds_read_b64 v[238:239], v150 offset:27648
	ds_read_b64 v[240:241], v151 offset:27648
	ds_read_b64 v[248:249], v152 offset:32256
	ds_read_b64 v[250:251], v153 offset:32256
	ds_read_b64 v[252:253], v154 offset:27648
	ds_read_b64 v[254:255], v155 offset:27648
	v_add_f32_e32 v4, v71, v5
	v_add_f32_e32 v3, v72, v4
	v_add_f32_e32 v166, v0, v3
	v_cvt_pk_bf16_f32 v2, v2, v51
	v_cvt_pk_bf16_f32 v3, v52, v53
	v_cvt_pk_bf16_f32 v4, v54, v55
	v_cvt_pk_bf16_f32 v5, v56, v57
	s_add_i32 s13, s13, 2
	s_addk_i32 s12, 0x80
	s_waitcnt lgkmcnt(8)
	v_mfma_f32_32x32x16_bf16 v[32:47], v[6:9], v[2:5], v[32:47]
	ds_read_b64 v[6:7], v156 offset:32256
	ds_read_b64 v[8:9], v157 offset:32256
	s_add_u32 s4, s4, 0xa0000
	s_addc_u32 s5, s5, 0
	s_cmp_lg_u32 s13, 5
	s_waitcnt lgkmcnt(8)
	v_mfma_f32_32x32x16_bf16 v[16:31], v[234:237], v[2:5], v[16:31]
	ds_read_b64 v[234:235], v158 offset:27648
	ds_read_b64 v[236:237], v159 offset:27648
	v_cvt_pk_bf16_f32 v2, v58, v59
	v_cvt_pk_bf16_f32 v3, v60, v61
	v_cvt_pk_bf16_f32 v4, v62, v63
	v_cvt_pk_bf16_f32 v5, v66, v65
	s_nop 0
	s_waitcnt lgkmcnt(8)
	v_mfma_f32_32x32x16_bf16 v[32:47], v[238:241], v[2:5], v[32:47]
	ds_read_b64 v[238:239], v164 offset:32256
	ds_read_b64 v[240:241], v165 offset:32256
	s_waitcnt lgkmcnt(8)
	v_mfma_f32_32x32x16_bf16 v[16:31], v[248:251], v[2:5], v[16:31]
	v_cvt_pk_bf16_f32 v2, v64, v49
	v_cvt_pk_bf16_f32 v3, v48, v15
	v_cvt_pk_bf16_f32 v4, v14, v13
	v_cvt_pk_bf16_f32 v5, v12, v11
	s_nop 0
	s_waitcnt lgkmcnt(6)
	v_mfma_f32_32x32x16_bf16 v[32:47], v[252:255], v[2:5], v[32:47]
	s_waitcnt lgkmcnt(4)
	v_mfma_f32_32x32x16_bf16 v[16:31], v[6:9], v[2:5], v[16:31]
	v_cvt_pk_bf16_f32 v2, v10, v67
	v_cvt_pk_bf16_f32 v3, v50, v68
	v_cvt_pk_bf16_f32 v4, v69, v70
	v_cvt_pk_bf16_f32 v5, v71, v72
	s_nop 0
	s_waitcnt lgkmcnt(2)
	v_mfma_f32_32x32x16_bf16 v[32:47], v[234:237], v[2:5], v[32:47]
	s_waitcnt lgkmcnt(0)
	v_mfma_f32_32x32x16_bf16 v[16:31], v[238:241], v[2:5], v[16:31]
	s_cbranch_scc0 .LBB0_775

.LBB0_767:
	s_waitcnt lgkmcnt(0)
	s_barrier
	ds_read_b128 v[2:5], v145
	ds_read_b128 v[6:9], v145 offset:32
	ds_read_b128 v[234:237], v145 offset:4608
	ds_read_b128 v[238:241], v145 offset:4640
	ds_read_b128 v[248:251], v145 offset:64
	ds_read_b128 v[252:255], v145 offset:4672
	s_waitcnt lgkmcnt(5)
	v_mfma_f32_32x32x16_bf16 v[64:79], v[2:5], v[80:83], 0
	ds_read_b128 v[2:5], v145 offset:96
	s_mov_b32 s10, 0xf149f2ca
	s_waitcnt lgkmcnt(4)
	v_mfma_f32_32x32x16_bf16 v[48:63], v[234:237], v[80:83], 0
	ds_read_b128 v[234:237], v145 offset:4704
	s_waitcnt lgkmcnt(4)
	v_mfma_f32_32x32x16_bf16 v[48:63], v[238:241], v[84:87], v[48:63]
	s_nop 0
	v_mfma_f32_32x32x16_bf16 v[64:79], v[6:9], v[84:87], v[64:79]
	s_waitcnt lgkmcnt(3)
	v_mfma_f32_32x32x16_bf16 v[64:79], v[248:251], v[88:91], v[64:79]
	s_waitcnt lgkmcnt(2)
	v_mfma_f32_32x32x16_bf16 v[48:63], v[252:255], v[88:91], v[48:63]
	s_waitcnt lgkmcnt(1)
	v_mfma_f32_32x32x16_bf16 v[64:79], v[2:5], v[92:95], v[64:79]
	s_waitcnt lgkmcnt(0)
	v_mfma_f32_32x32x16_bf16 v[48:63], v[234:237], v[92:95], v[48:63]
	s_nop 8
	v_mul_f32_e32 v3, 0x3e38aa3b, v64
	v_mul_f32_e32 v4, 0x3e38aa3b, v65
	v_max3_f32 v2, v3, s10, v4
	v_mul_f32_e32 v5, 0x3e38aa3b, v66
	v_mul_f32_e32 v6, 0x3e38aa3b, v67
	v_max3_f32 v2, v2, v5, v6
	v_mul_f32_e32 v7, 0x3e38aa3b, v68
	v_mul_f32_e32 v8, 0x3e38aa3b, v69
	v_max3_f32 v2, v2, v7, v8
	v_mul_f32_e32 v9, 0x3e38aa3b, v70
	v_mul_f32_e32 v10, 0x3e38aa3b, v71
	v_max3_f32 v2, v2, v9, v10
	v_mul_f32_e32 v11, 0x3e38aa3b, v72
	v_mul_f32_e32 v12, 0x3e38aa3b, v73
	v_max3_f32 v2, v2, v11, v12
	v_mul_f32_e32 v13, 0x3e38aa3b, v74
	v_mul_f32_e32 v14, 0x3e38aa3b, v75
	v_max3_f32 v2, v2, v13, v14
	v_mul_f32_e32 v15, 0x3e38aa3b, v76
	v_mul_f32_e32 v74, 0x3e38aa3b, v77
	v_max3_f32 v2, v2, v15, v74
	v_mul_f32_e32 v75, 0x3e38aa3b, v78
	v_mul_f32_e32 v71, 0x3e38aa3b, v79
	v_max3_f32 v2, v2, v75, v71
	v_mul_f32_e32 v170, 0x3e38aa3b, v48
	v_mul_f32_e32 v168, 0x3e38aa3b, v49
	v_max3_f32 v2, v2, v170, v168
	v_mul_f32_e32 v169, 0x3e38aa3b, v50
	v_mul_f32_e32 v78, 0x3e38aa3b, v51
	v_max3_f32 v2, v2, v169, v78
	v_mul_f32_e32 v79, 0x3e38aa3b, v52
	v_mul_f32_e32 v76, 0x3e38aa3b, v53
	v_max3_f32 v2, v2, v79, v76
	v_mul_f32_e32 v77, 0x3e38aa3b, v54
	v_mul_f32_e32 v72, 0x3e38aa3b, v55
	v_max3_f32 v2, v2, v77, v72
	v_mul_f32_e32 v73, 0x3e38aa3b, v56
	v_mul_f32_e32 v69, 0x3e38aa3b, v57
	v_max3_f32 v2, v2, v73, v69
	v_mul_f32_e32 v70, 0x3e38aa3b, v58
	v_mul_f32_e32 v67, 0x3e38aa3b, v59
	v_max3_f32 v2, v2, v70, v67
	v_mul_f32_e32 v68, 0x3e38aa3b, v60
	v_mul_f32_e32 v64, 0x3e38aa3b, v61
	v_max3_f32 v2, v2, v68, v64
	v_mul_f32_e32 v65, 0x3e38aa3b, v62
	v_mul_f32_e32 v66, 0x3e38aa3b, v63
	v_max3_f32 v2, v2, v65, v66
	ds_bpermute_b32 v48, v142, v2
	s_waitcnt lgkmcnt(0)
	v_max3_f32 v2, v167, v2, v48
	v_cmp_gt_f32_e32 vcc, v2, v167
	s_cbranch_vccz .LBB0_770
	v_sub_f32_e32 v48, v167, v2
	v_exp_f32_e32 v48, v48
	s_nop 0
	v_mul_f32_e32 v166, v166, v48
	v_pk_mul_f32 v[46:47], v[46:47], v[48:49] op_sel_hi:[1,0]
	v_pk_mul_f32 v[44:45], v[44:45], v[48:49] op_sel_hi:[1,0]
	v_pk_mul_f32 v[42:43], v[42:43], v[48:49] op_sel_hi:[1,0]
	v_pk_mul_f32 v[40:41], v[40:41], v[48:49] op_sel_hi:[1,0]
	v_pk_mul_f32 v[38:39], v[38:39], v[48:49] op_sel_hi:[1,0]
	v_pk_mul_f32 v[36:37], v[36:37], v[48:49] op_sel_hi:[1,0]
	v_pk_mul_f32 v[34:35], v[34:35], v[48:49] op_sel_hi:[1,0]
	v_pk_mul_f32 v[32:33], v[32:33], v[48:49] op_sel_hi:[1,0]
	v_pk_mul_f32 v[30:31], v[30:31], v[48:49] op_sel_hi:[1,0]
	v_pk_mul_f32 v[28:29], v[28:29], v[48:49] op_sel_hi:[1,0]
	v_pk_mul_f32 v[26:27], v[26:27], v[48:49] op_sel_hi:[1,0]
	v_pk_mul_f32 v[24:25], v[24:25], v[48:49] op_sel_hi:[1,0]
	v_pk_mul_f32 v[22:23], v[22:23], v[48:49] op_sel_hi:[1,0]
	v_pk_mul_f32 v[20:21], v[20:21], v[48:49] op_sel_hi:[1,0]
	v_pk_mul_f32 v[18:19], v[18:19], v[48:49] op_sel_hi:[1,0]
	v_pk_mul_f32 v[16:17], v[16:17], v[48:49] op_sel_hi:[1,0]
	s_branch .LBB0_771

.LBB0_771:
	v_sub_f32_e32 v3, v3, v2
	v_sub_f32_e32 v4, v4, v2
	v_sub_f32_e32 v5, v5, v2
	v_sub_f32_e32 v6, v6, v2
	v_sub_f32_e32 v7, v7, v2
	v_sub_f32_e32 v8, v8, v2
	v_sub_f32_e32 v9, v9, v2
	v_sub_f32_e32 v10, v10, v2
	v_exp_f32_e32 v3, v3
	v_exp_f32_e32 v4, v4
	v_exp_f32_e32 v5, v5
	v_exp_f32_e32 v6, v6
	v_exp_f32_e32 v7, v7
	v_exp_f32_e32 v8, v8
	v_exp_f32_e32 v9, v9
	v_exp_f32_e32 v10, v10
	v_sub_f32_e32 v48, v74, v2
	v_sub_f32_e32 v49, v75, v2
	v_sub_f32_e32 v58, v72, v2
	v_sub_f32_e32 v59, v73, v2
	ds_read_b64 v[72:73], v146 offset:9216
	ds_read_b64 v[74:75], v147 offset:9216
	ds_read_b64 v[234:235], v148 offset:13824
	ds_read_b64 v[236:237], v149 offset:13824
	ds_read_b64 v[238:239], v150 offset:9216
	ds_read_b64 v[240:241], v151 offset:9216
	ds_read_b64 v[248:249], v152 offset:13824
	ds_read_b64 v[250:251], v153 offset:13824
	ds_read_b64 v[252:253], v154 offset:9216
	ds_read_b64 v[254:255], v155 offset:9216
	v_sub_f32_e32 v50, v71, v2
	v_sub_f32_e32 v60, v69, v2
	v_sub_f32_e32 v61, v70, v2
	v_sub_f32_e32 v63, v68, v2
	v_cvt_pk_bf16_f32 v68, v3, v4
	v_cvt_pk_bf16_f32 v69, v5, v6
	v_cvt_pk_bf16_f32 v70, v7, v8
	v_cvt_pk_bf16_f32 v71, v9, v10
	v_sub_f32_e32 v11, v11, v2
	v_sub_f32_e32 v12, v12, v2
	s_waitcnt lgkmcnt(8)
	v_mfma_f32_32x32x16_bf16 v[32:47], v[72:75], v[68:71], v[32:47]
	ds_read_b64 v[72:73], v156 offset:13824
	ds_read_b64 v[74:75], v157 offset:13824
	v_sub_f32_e32 v13, v13, v2
	v_sub_f32_e32 v14, v14, v2
	v_sub_f32_e32 v15, v15, v2
	v_exp_f32_e32 v11, v11
	v_exp_f32_e32 v12, v12
	v_exp_f32_e32 v13, v13
	v_exp_f32_e32 v14, v14
	v_exp_f32_e32 v15, v15
	v_exp_f32_e32 v48, v48
	v_exp_f32_e32 v49, v49
	v_exp_f32_e32 v50, v50
	s_waitcnt lgkmcnt(8)
	v_mfma_f32_32x32x16_bf16 v[16:31], v[234:237], v[68:71], v[16:31]
	ds_read_b64 v[234:235], v158 offset:9216
	ds_read_b64 v[236:237], v159 offset:9216
	v_cvt_pk_bf16_f32 v68, v11, v12
	v_cvt_pk_bf16_f32 v69, v13, v14
	v_cvt_pk_bf16_f32 v70, v15, v48
	v_cvt_pk_bf16_f32 v71, v49, v50
	v_sub_f32_e32 v51, v170, v2
	v_sub_f32_e32 v52, v168, v2
	s_waitcnt lgkmcnt(8)
	v_mfma_f32_32x32x16_bf16 v[32:47], v[238:241], v[68:71], v[32:47]
	ds_read_b64 v[238:239], v164 offset:13824
	ds_read_b64 v[240:241], v165 offset:13824
	v_sub_f32_e32 v53, v169, v2
	v_sub_f32_e32 v54, v78, v2
	v_sub_f32_e32 v55, v79, v2
	v_sub_f32_e32 v56, v76, v2
	v_sub_f32_e32 v57, v77, v2
	v_exp_f32_e32 v51, v51
	v_exp_f32_e32 v52, v52
	v_exp_f32_e32 v53, v53
	v_exp_f32_e32 v54, v54
	v_exp_f32_e32 v55, v55
	v_exp_f32_e32 v56, v56
	v_exp_f32_e32 v57, v57
	v_exp_f32_e32 v58, v58
	s_waitcnt lgkmcnt(8)
	v_mfma_f32_32x32x16_bf16 v[16:31], v[248:251], v[68:71], v[16:31]
	v_cvt_pk_bf16_f32 v68, v51, v52
	v_cvt_pk_bf16_f32 v69, v53, v54
	v_cvt_pk_bf16_f32 v70, v55, v56
	v_cvt_pk_bf16_f32 v71, v57, v58
	v_sub_f32_e32 v62, v67, v2
	v_sub_f32_e32 v64, v64, v2
	s_waitcnt lgkmcnt(6)
	v_mfma_f32_32x32x16_bf16 v[32:47], v[252:255], v[68:71], v[32:47]
	v_sub_f32_e32 v65, v65, v2
	v_sub_f32_e32 v66, v66, v2
	v_exp_f32_e32 v59, v59
	v_exp_f32_e32 v60, v60
	v_exp_f32_e32 v61, v61
	v_exp_f32_e32 v62, v62
	v_exp_f32_e32 v63, v63
	v_exp_f32_e32 v64, v64
	v_exp_f32_e32 v65, v65
	v_exp_f32_e32 v66, v66
	s_waitcnt lgkmcnt(4)
	v_mfma_f32_32x32x16_bf16 v[16:31], v[72:75], v[68:71], v[16:31]
	v_cvt_pk_bf16_f32 v68, v59, v60
	v_cvt_pk_bf16_f32 v69, v61, v62
	v_cvt_pk_bf16_f32 v70, v63, v64
	v_cvt_pk_bf16_f32 v71, v65, v66
	v_add_u32_e32 v67, 0x4800, v143
	s_cmp_lt_u32 s13, 2
	s_waitcnt lgkmcnt(2)
	v_mfma_f32_32x32x16_bf16 v[32:47], v[234:237], v[68:71], v[32:47]
	s_waitcnt vmcnt(5)
	ds_write2_b64 v67, v[126:127], v[130:131] offset1:18
	s_waitcnt vmcnt(1)
	ds_write2_b64 v67, v[134:135], v[138:139] offset0:36 offset1:54
	s_waitcnt vmcnt(0)
	v_lshlrev_b32_e32 v67, 16, v140
	s_cselect_b64 s[10:11], -1, 0
	s_cmp_gt_u32 s13, 1
	s_waitcnt lgkmcnt(2)
	v_mfma_f32_32x32x16_bf16 v[16:31], v[238:241], v[68:71], v[16:31]
	v_lshlrev_b32_e32 v68, 16, v132
	v_or_b32_sdwa v69, v136, v67 dst_sel:DWORD dst_unused:UNUSED_PAD src0_sel:WORD_0 src1_sel:DWORD
	v_and_b32_e32 v67, 0xffff0000, v140
	v_and_b32_e32 v70, 0xffff0000, v132
	v_or_b32_sdwa v68, v128, v68 dst_sel:DWORD dst_unused:UNUSED_PAD src0_sel:WORD_0 src1_sel:DWORD
	v_or_b32_sdwa v71, v136, v67 dst_sel:DWORD dst_unused:UNUSED_PAD src0_sel:WORD_1 src1_sel:DWORD
	v_or_b32_sdwa v70, v128, v70 dst_sel:DWORD dst_unused:UNUSED_PAD src0_sel:WORD_1 src1_sel:DWORD
	v_add_u32_e32 v67, 0x6800, v144
	ds_write2_b64 v67, v[68:69], v[70:71] offset0:128 offset1:146
	v_lshlrev_b32_e32 v68, 16, v141
	v_lshlrev_b32_e32 v70, 16, v133
	v_or_b32_sdwa v69, v137, v68 dst_sel:DWORD dst_unused:UNUSED_PAD src0_sel:WORD_0 src1_sel:DWORD
	v_or_b32_sdwa v68, v129, v70 dst_sel:DWORD dst_unused:UNUSED_PAD src0_sel:WORD_0 src1_sel:DWORD
	v_and_b32_e32 v70, 0xffff0000, v141
	v_and_b32_e32 v72, 0xffff0000, v133
	v_or_b32_sdwa v71, v137, v70 dst_sel:DWORD dst_unused:UNUSED_PAD src0_sel:WORD_1 src1_sel:DWORD
	v_or_b32_sdwa v70, v129, v72 dst_sel:DWORD dst_unused:UNUSED_PAD src0_sel:WORD_1 src1_sel:DWORD
	ds_write2_b64 v67, v[68:69], v[70:71] offset0:164 offset1:182
	s_cbranch_scc1 .LBB0_773
	s_add_u32 s8, s4, 0x200
	s_addc_u32 s9, s5, 0
	s_mov_b64 s[6:7], s[4:5]

.LBB0_780:
	v_sub_f32_e32 v2, v174, v167
	v_exp_f32_e32 v2, v2
	v_sub_f32_e32 v51, v173, v167
	v_exp_f32_e32 v51, v51
	v_sub_f32_e32 v52, v172, v167
	v_exp_f32_e32 v52, v52
	v_sub_f32_e32 v53, v171, v167
	v_exp_f32_e32 v53, v53
	v_sub_f32_e32 v54, v170, v167
	v_add_f32_e32 v50, 0, v2
	v_exp_f32_e32 v54, v54
	v_sub_f32_e32 v55, v169, v167
	v_add_f32_e32 v50, v51, v50
	v_exp_f32_e32 v55, v55
	v_sub_f32_e32 v56, v168, v167
	v_add_f32_e32 v50, v52, v50
	v_exp_f32_e32 v56, v56
	v_sub_f32_e32 v57, v166, v167
	v_add_f32_e32 v50, v53, v50
	v_exp_f32_e32 v57, v57
	v_sub_f32_e32 v58, v72, v167
	v_add_f32_e32 v50, v54, v50
	v_exp_f32_e32 v58, v58
	v_sub_f32_e32 v59, v71, v167
	v_add_f32_e32 v50, v55, v50
	v_exp_f32_e32 v59, v59
	v_sub_f32_e32 v60, v70, v167
	v_add_f32_e32 v50, v56, v50
	v_exp_f32_e32 v60, v60
	v_sub_f32_e32 v61, v69, v167
	v_add_f32_e32 v50, v57, v50
	v_exp_f32_e32 v61, v61
	v_sub_f32_e32 v62, v68, v167
	v_add_f32_e32 v50, v58, v50
	v_exp_f32_e32 v62, v62
	v_sub_f32_e32 v63, v67, v167
	v_add_f32_e32 v50, v59, v50
	v_exp_f32_e32 v63, v63
	v_sub_f32_e32 v66, v66, v167
	v_add_f32_e32 v50, v60, v50
	v_exp_f32_e32 v66, v66
	v_sub_f32_e32 v65, v65, v167
	v_add_f32_e32 v50, v61, v50
	v_exp_f32_e32 v65, v65
	v_sub_f32_e32 v64, v64, v167
	v_add_f32_e32 v50, v62, v50
	v_exp_f32_e32 v64, v64
	v_sub_f32_e32 v49, v49, v167
	v_add_f32_e32 v50, v63, v50
	v_exp_f32_e32 v49, v49
	v_sub_f32_e32 v48, v48, v167
	v_add_f32_e32 v50, v66, v50
	v_exp_f32_e32 v48, v48
	v_sub_f32_e32 v15, v15, v167
	v_add_f32_e32 v50, v65, v50
	v_exp_f32_e32 v15, v15
	v_sub_f32_e32 v14, v14, v167
	v_add_f32_e32 v50, v64, v50
	v_exp_f32_e32 v14, v14
	v_sub_f32_e32 v13, v13, v167
	v_add_f32_e32 v50, v49, v50
	v_exp_f32_e32 v13, v13
	v_sub_f32_e32 v12, v12, v167
	v_add_f32_e32 v50, v48, v50
	v_exp_f32_e32 v12, v12
	v_sub_f32_e32 v11, v11, v167
	v_add_f32_e32 v50, v15, v50
	v_exp_f32_e32 v11, v11
	v_sub_f32_e32 v10, v10, v167
	v_add_f32_e32 v50, v14, v50
	v_exp_f32_e32 v10, v10
	v_sub_f32_e32 v9, v9, v167
	v_add_f32_e32 v50, v13, v50
	v_exp_f32_e32 v67, v9
	v_add_f32_e32 v50, v12, v50
	v_add_f32_e32 v50, v11, v50
	v_add_f32_e32 v50, v10, v50
	v_sub_f32_e32 v8, v8, v167
	v_add_f32_e32 v9, v67, v50
	v_exp_f32_e32 v50, v8
	v_sub_f32_e32 v7, v7, v167
	v_exp_f32_e32 v68, v7
	v_sub_f32_e32 v6, v6, v167
	v_exp_f32_e32 v69, v6
	v_sub_f32_e32 v5, v5, v167
	v_exp_f32_e32 v70, v5
	v_add_f32_e32 v8, v50, v9
	v_sub_f32_e32 v4, v4, v167
	v_add_f32_e32 v7, v68, v8
	v_exp_f32_e32 v71, v4
	v_sub_f32_e32 v3, v3, v167
	v_add_f32_e32 v6, v69, v7
	v_exp_f32_e32 v72, v3
	v_add_f32_e32 v5, v70, v6
	ds_read_b64 v[6:7], v146 offset:27648
	ds_read_b64 v[8:9], v147 offset:27648
	ds_read_b64 v[234:235], v148 offset:32256
	ds_read_b64 v[236:237], v149 offset:32256
	ds_read_b64 v[238:239], v150 offset:27648
	ds_read_b64 v[240:241], v151 offset:27648
	ds_read_b64 v[248:249], v152 offset:32256
	ds_read_b64 v[250:251], v153 offset:32256
	ds_read_b64 v[252:253], v154 offset:27648
	ds_read_b64 v[254:255], v155 offset:27648
	v_add_f32_e32 v4, v71, v5
	v_add_f32_e32 v3, v72, v4
	v_add_f32_e32 v166, v0, v3
	v_cvt_pk_bf16_f32 v2, v2, v51
	v_cvt_pk_bf16_f32 v3, v52, v53
	v_cvt_pk_bf16_f32 v4, v54, v55
	v_cvt_pk_bf16_f32 v5, v56, v57
	s_add_u32 s8, s8, 0xa0000
	s_addc_u32 s9, s9, 0
	s_waitcnt lgkmcnt(8)
	v_mfma_f32_32x32x16_bf16 v[32:47], v[6:9], v[2:5], v[32:47]
	ds_read_b64 v[6:7], v156 offset:32256
	ds_read_b64 v[8:9], v157 offset:32256
	s_add_i32 s34, s34, 2
	s_cmp_lg_u32 s8, 0x140000
	s_waitcnt lgkmcnt(8)
	v_mfma_f32_32x32x16_bf16 v[16:31], v[234:237], v[2:5], v[16:31]
	ds_read_b64 v[234:235], v158 offset:27648
	ds_read_b64 v[236:237], v159 offset:27648
	v_cvt_pk_bf16_f32 v2, v58, v59
	v_cvt_pk_bf16_f32 v3, v60, v61
	v_cvt_pk_bf16_f32 v4, v62, v63
	v_cvt_pk_bf16_f32 v5, v66, v65
	s_nop 0
	s_waitcnt lgkmcnt(8)
	v_mfma_f32_32x32x16_bf16 v[32:47], v[238:241], v[2:5], v[32:47]
	ds_read_b64 v[238:239], v164 offset:32256
	ds_read_b64 v[240:241], v165 offset:32256
	s_waitcnt lgkmcnt(8)
	v_mfma_f32_32x32x16_bf16 v[16:31], v[248:251], v[2:5], v[16:31]
	v_cvt_pk_bf16_f32 v2, v64, v49
	v_cvt_pk_bf16_f32 v3, v48, v15
	v_cvt_pk_bf16_f32 v4, v14, v13
	v_cvt_pk_bf16_f32 v5, v12, v11
	s_nop 0
	s_waitcnt lgkmcnt(6)
	v_mfma_f32_32x32x16_bf16 v[32:47], v[252:255], v[2:5], v[32:47]
	s_waitcnt lgkmcnt(4)
	v_mfma_f32_32x32x16_bf16 v[16:31], v[6:9], v[2:5], v[16:31]
	v_cvt_pk_bf16_f32 v2, v10, v67
	v_cvt_pk_bf16_f32 v3, v50, v68
	v_cvt_pk_bf16_f32 v4, v69, v70
	v_cvt_pk_bf16_f32 v5, v71, v72
	s_nop 0
	s_waitcnt lgkmcnt(2)
	v_mfma_f32_32x32x16_bf16 v[32:47], v[234:237], v[2:5], v[32:47]
	s_waitcnt lgkmcnt(0)
	v_mfma_f32_32x32x16_bf16 v[16:31], v[238:241], v[2:5], v[16:31]
	s_cbranch_scc0 .LBB0_793

.LBB0_789:
	v_sub_f32_e32 v3, v3, v2
	v_sub_f32_e32 v4, v4, v2
	v_sub_f32_e32 v5, v5, v2
	v_sub_f32_e32 v6, v6, v2
	v_sub_f32_e32 v7, v7, v2
	v_sub_f32_e32 v8, v8, v2
	v_sub_f32_e32 v9, v9, v2
	v_sub_f32_e32 v10, v10, v2
	v_exp_f32_e32 v3, v3
	v_exp_f32_e32 v4, v4
	v_exp_f32_e32 v5, v5
	v_exp_f32_e32 v6, v6
	v_exp_f32_e32 v7, v7
	v_exp_f32_e32 v8, v8
	v_exp_f32_e32 v9, v9
	v_exp_f32_e32 v10, v10
	v_sub_f32_e32 v48, v74, v2
	v_sub_f32_e32 v49, v75, v2
	v_sub_f32_e32 v58, v72, v2
	v_sub_f32_e32 v59, v73, v2
	ds_read_b64 v[72:73], v146 offset:9216
	ds_read_b64 v[74:75], v147 offset:9216
	ds_read_b64 v[234:235], v148 offset:13824
	ds_read_b64 v[236:237], v149 offset:13824
	ds_read_b64 v[238:239], v150 offset:9216
	ds_read_b64 v[240:241], v151 offset:9216
	ds_read_b64 v[248:249], v152 offset:13824
	ds_read_b64 v[250:251], v153 offset:13824
	ds_read_b64 v[252:253], v154 offset:9216
	ds_read_b64 v[254:255], v155 offset:9216
	v_sub_f32_e32 v50, v71, v2
	v_sub_f32_e32 v60, v69, v2
	v_sub_f32_e32 v61, v70, v2
	v_sub_f32_e32 v63, v68, v2
	v_cvt_pk_bf16_f32 v68, v3, v4
	v_cvt_pk_bf16_f32 v69, v5, v6
	v_cvt_pk_bf16_f32 v70, v7, v8
	v_cvt_pk_bf16_f32 v71, v9, v10
	v_sub_f32_e32 v11, v11, v2
	v_sub_f32_e32 v12, v12, v2
	s_waitcnt lgkmcnt(8)
	v_mfma_f32_32x32x16_bf16 v[32:47], v[72:75], v[68:71], v[32:47]
	ds_read_b64 v[72:73], v156 offset:13824
	ds_read_b64 v[74:75], v157 offset:13824
	v_sub_f32_e32 v13, v13, v2
	v_sub_f32_e32 v14, v14, v2
	v_sub_f32_e32 v15, v15, v2
	v_exp_f32_e32 v11, v11
	v_exp_f32_e32 v12, v12
	v_exp_f32_e32 v13, v13
	v_exp_f32_e32 v14, v14
	v_exp_f32_e32 v15, v15
	v_exp_f32_e32 v48, v48
	v_exp_f32_e32 v49, v49
	v_exp_f32_e32 v50, v50
	s_waitcnt lgkmcnt(8)
	v_mfma_f32_32x32x16_bf16 v[16:31], v[234:237], v[68:71], v[16:31]
	ds_read_b64 v[234:235], v158 offset:9216
	ds_read_b64 v[236:237], v159 offset:9216
	v_cvt_pk_bf16_f32 v68, v11, v12
	v_cvt_pk_bf16_f32 v69, v13, v14
	v_cvt_pk_bf16_f32 v70, v15, v48
	v_cvt_pk_bf16_f32 v71, v49, v50
	v_sub_f32_e32 v51, v170, v2
	v_sub_f32_e32 v52, v168, v2
	s_waitcnt lgkmcnt(8)
	v_mfma_f32_32x32x16_bf16 v[32:47], v[238:241], v[68:71], v[32:47]
	ds_read_b64 v[238:239], v164 offset:13824
	ds_read_b64 v[240:241], v165 offset:13824
	v_sub_f32_e32 v53, v169, v2
	v_sub_f32_e32 v54, v78, v2
	v_sub_f32_e32 v55, v79, v2
	v_sub_f32_e32 v56, v76, v2
	v_sub_f32_e32 v57, v77, v2
	v_exp_f32_e32 v51, v51
	v_exp_f32_e32 v52, v52
	v_exp_f32_e32 v53, v53
	v_exp_f32_e32 v54, v54
	v_exp_f32_e32 v55, v55
	v_exp_f32_e32 v56, v56
	v_exp_f32_e32 v57, v57
	v_exp_f32_e32 v58, v58
	s_waitcnt lgkmcnt(8)
	v_mfma_f32_32x32x16_bf16 v[16:31], v[248:251], v[68:71], v[16:31]
	v_cvt_pk_bf16_f32 v68, v51, v52
	v_cvt_pk_bf16_f32 v69, v53, v54
	v_cvt_pk_bf16_f32 v70, v55, v56
	v_cvt_pk_bf16_f32 v71, v57, v58
	v_sub_f32_e32 v62, v67, v2
	v_sub_f32_e32 v64, v64, v2
	s_waitcnt lgkmcnt(6)
	v_mfma_f32_32x32x16_bf16 v[32:47], v[252:255], v[68:71], v[32:47]
	v_sub_f32_e32 v65, v65, v2
	v_sub_f32_e32 v66, v66, v2
	v_exp_f32_e32 v59, v59
	v_exp_f32_e32 v60, v60
	v_exp_f32_e32 v61, v61
	v_exp_f32_e32 v62, v62
	v_exp_f32_e32 v63, v63
	v_exp_f32_e32 v64, v64
	v_exp_f32_e32 v65, v65
	v_exp_f32_e32 v66, v66
	s_waitcnt lgkmcnt(4)
	v_mfma_f32_32x32x16_bf16 v[16:31], v[72:75], v[68:71], v[16:31]
	v_cvt_pk_bf16_f32 v68, v59, v60
	v_cvt_pk_bf16_f32 v69, v61, v62
	v_cvt_pk_bf16_f32 v70, v63, v64
	v_cvt_pk_bf16_f32 v71, v65, v66
	v_add_u32_e32 v67, 0x4800, v143
	s_cmp_lt_u32 s34, 2
	s_waitcnt lgkmcnt(2)
	v_mfma_f32_32x32x16_bf16 v[32:47], v[234:237], v[68:71], v[32:47]
	s_waitcnt vmcnt(5)
	ds_write2_b64 v67, v[126:127], v[130:131] offset1:18
	s_waitcnt vmcnt(1)
	ds_write2_b64 v67, v[134:135], v[138:139] offset0:36 offset1:54
	s_waitcnt vmcnt(0)
	v_lshlrev_b32_e32 v67, 16, v140
	s_cselect_b64 s[10:11], -1, 0
	s_cmp_gt_u32 s34, 1
	s_waitcnt lgkmcnt(2)
	v_mfma_f32_32x32x16_bf16 v[16:31], v[238:241], v[68:71], v[16:31]
	v_lshlrev_b32_e32 v68, 16, v132
	v_or_b32_sdwa v69, v136, v67 dst_sel:DWORD dst_unused:UNUSED_PAD src0_sel:WORD_0 src1_sel:DWORD
	v_and_b32_e32 v67, 0xffff0000, v140
	v_and_b32_e32 v70, 0xffff0000, v132
	v_or_b32_sdwa v68, v128, v68 dst_sel:DWORD dst_unused:UNUSED_PAD src0_sel:WORD_0 src1_sel:DWORD
	v_or_b32_sdwa v71, v136, v67 dst_sel:DWORD dst_unused:UNUSED_PAD src0_sel:WORD_1 src1_sel:DWORD
	v_or_b32_sdwa v70, v128, v70 dst_sel:DWORD dst_unused:UNUSED_PAD src0_sel:WORD_1 src1_sel:DWORD
	v_add_u32_e32 v67, 0x6800, v144
	ds_write2_b64 v67, v[68:69], v[70:71] offset0:128 offset1:146
	v_lshlrev_b32_e32 v68, 16, v141
	v_lshlrev_b32_e32 v70, 16, v133
	v_or_b32_sdwa v69, v137, v68 dst_sel:DWORD dst_unused:UNUSED_PAD src0_sel:WORD_0 src1_sel:DWORD
	v_or_b32_sdwa v68, v129, v70 dst_sel:DWORD dst_unused:UNUSED_PAD src0_sel:WORD_0 src1_sel:DWORD
	v_and_b32_e32 v70, 0xffff0000, v141
	v_and_b32_e32 v72, 0xffff0000, v133
	v_or_b32_sdwa v71, v137, v70 dst_sel:DWORD dst_unused:UNUSED_PAD src0_sel:WORD_1 src1_sel:DWORD
	v_or_b32_sdwa v70, v129, v72 dst_sel:DWORD dst_unused:UNUSED_PAD src0_sel:WORD_1 src1_sel:DWORD
	ds_write2_b64 v67, v[68:69], v[70:71] offset0:164 offset1:182
	s_cbranch_scc1 .LBB0_791
	s_add_u32 s6, s13, s8
	s_addc_u32 s7, s14, s9
	s_add_u32 s4, s6, 0xfa6f0400
	s_addc_u32 s5, s7, -1
	s_add_u32 s6, s6, 0xfa6f0500
	s_addc_u32 s7, s7, -1
